# P2 epilogue: the x1.0 scale multiplies are skipped for the ten non-q column panels (only pn = 0 needs the 1/8 scale)
# speedup vs baseline: 1.0020x; 1.0020x over previous
; __device__ __forceinline__ unsigned cvt_pk_bf16(float lo, float hi) { unsigned r; asm volatile("v_cvt_pk_bf16_f32 %0, %1, %2" : "=v"(r) : "v"(lo), "v"(hi)); return r; }
; __device__ __forceinline__ float silu_f(float x) { return x * __builtin_amdgcn_rcpf(1.0f + __expf(-x)); }
;     __device__ __forceinline__ void operator()(const f32x4 (&acc)[2][2][4][2], const Unit& u, int wr, int wc, int fr, int fq) const {
;     ...
;             const int col0 = u.pn * BM + bj * HALF + wc * 32 + 8 * fq;
;             if (col0 >= 2880) continue;
;             const float sc = (col0 < 256) ? 0.125f : 1.0f;
; #pragma unroll
;             for (int ai = 0; ai < 2; ++ai)
; #pragma unroll
;                 for (int m = 0; m < 4; ++m) {
;                     f32x4 v0 = acc[ai][bj][m][0] * sc, v1 = acc[ai][bj][m][1] * sc;
;                     if (col0 >= 1024 && col0 < 2048) {
; #pragma unroll
;                         for (int e = 0; e < 4; ++e) { v0[e] = silu_f(v0[e]); v1[e] = silu_f(v1[e]); } }
;                     u32x4 w; w.x = cvt_pk_bf16(v0[0], v0[1]); w.y = cvt_pk_bf16(v0[2], v0[3]); w.z = cvt_pk_bf16(v1[0], v1[1]); w.w = cvt_pk_bf16(v1[2], v1[3]);
;                     *(u32x4*)(O + (size_t)(row0 + ai * HALF + m * 16) * 2880 + col0) = w;
.LBB0_273:
	s_cmp_eq_u32 s86, 0
	s_cselect_b64 s[88:89], -1, 0
	s_cselect_b32 s0, 0x3e000000, 1.0
	v_mov_b32_e32 v158, s0
	v_mov_b32_e32 v159, s0
	s_mov_b32 s0, 0xbfb8aa3b
	v_mov_b32_e32 v164, s0
	v_mov_b32_e32 v165, s0
	s_and_b32 s0, s86, 0xfffffc
	s_cmp_eq_u32 s0, 4
	s_cselect_b64 s[90:91], -1, 0
	v_lshl_add_u32 v156, s6, 8, v1
	v_lshl_or_b32 v162, s86, 8, v151
	v_mov_b64_e32 v[160:161], s[18:19]
	v_mad_i64_i32 v[160:161], s[0:1], v156, s95, v[160:161]
	v_lshlrev_b32_e32 v162, 1, v162
	v_mov_b32_e32 v163, 0
	v_lshl_add_u64 v[160:161], v[160:161], 0, v[162:163]
	s_mov_b32 s1, 0
	s_and_b64 vcc, exec, s[88:89]
	s_cbranch_vccz .Lp2q_nsc0
	v_pk_mul_f32 v[126:127], v[158:159], v[126:127]
	v_pk_mul_f32 v[128:129], v[158:159], v[128:129]
	v_pk_mul_f32 v[122:123], v[158:159], v[122:123]
	v_pk_mul_f32 v[124:125], v[158:159], v[124:125]
	v_pk_mul_f32 v[62:63], v[158:159], v[62:63]
	v_pk_mul_f32 v[64:65], v[158:159], v[64:65]
	v_pk_mul_f32 v[58:59], v[158:159], v[58:59]
	v_pk_mul_f32 v[60:61], v[158:159], v[60:61]
.Lp2q_nsc0:
	s_and_b64 vcc, exec, s[90:91]
	s_cbranch_vccz .Lp2q_ns0
	v_pk_mul_f32 v[166:167], v[126:127], v[164:165]
	v_pk_mul_f32 v[168:169], v[128:129], v[164:165]
	v_pk_mul_f32 v[170:171], v[122:123], v[164:165]
	v_pk_mul_f32 v[172:173], v[124:125], v[164:165]
	v_pk_mul_f32 v[174:175], v[62:63], v[164:165]
	v_pk_mul_f32 v[176:177], v[64:65], v[164:165]
	v_pk_mul_f32 v[178:179], v[58:59], v[164:165]
	v_pk_mul_f32 v[180:181], v[60:61], v[164:165]
	v_exp_f32_e32 v166, v166
	v_exp_f32_e32 v167, v167
	v_exp_f32_e32 v168, v168
	v_exp_f32_e32 v169, v169
	v_exp_f32_e32 v170, v170
	v_exp_f32_e32 v171, v171
	v_exp_f32_e32 v172, v172
	v_exp_f32_e32 v173, v173
	v_exp_f32_e32 v174, v174
	v_exp_f32_e32 v175, v175
	v_exp_f32_e32 v176, v176
	v_exp_f32_e32 v177, v177
	v_exp_f32_e32 v178, v178
	v_exp_f32_e32 v179, v179
	v_exp_f32_e32 v180, v180
	v_exp_f32_e32 v181, v181
	v_pk_add_f32 v[166:167], v[166:167], 1.0 op_sel_hi:[1,0]
	v_pk_add_f32 v[168:169], v[168:169], 1.0 op_sel_hi:[1,0]
	v_pk_add_f32 v[170:171], v[170:171], 1.0 op_sel_hi:[1,0]
	v_pk_add_f32 v[172:173], v[172:173], 1.0 op_sel_hi:[1,0]
	v_pk_add_f32 v[174:175], v[174:175], 1.0 op_sel_hi:[1,0]
	v_pk_add_f32 v[176:177], v[176:177], 1.0 op_sel_hi:[1,0]
	v_pk_add_f32 v[178:179], v[178:179], 1.0 op_sel_hi:[1,0]
	v_pk_add_f32 v[180:181], v[180:181], 1.0 op_sel_hi:[1,0]
	v_rcp_f32_e32 v166, v166
	v_rcp_f32_e32 v167, v167
	v_rcp_f32_e32 v168, v168
	v_rcp_f32_e32 v169, v169
	v_rcp_f32_e32 v170, v170
	v_rcp_f32_e32 v171, v171
	v_rcp_f32_e32 v172, v172
	v_rcp_f32_e32 v173, v173
	v_rcp_f32_e32 v174, v174
	v_rcp_f32_e32 v175, v175
	v_rcp_f32_e32 v176, v176
	v_rcp_f32_e32 v177, v177
	v_rcp_f32_e32 v178, v178
	v_rcp_f32_e32 v179, v179
	v_rcp_f32_e32 v180, v180
	v_rcp_f32_e32 v181, v181
	v_pk_mul_f32 v[126:127], v[126:127], v[166:167]
	v_pk_mul_f32 v[128:129], v[128:129], v[168:169]
	v_pk_mul_f32 v[122:123], v[122:123], v[170:171]
	v_pk_mul_f32 v[124:125], v[124:125], v[172:173]
	v_pk_mul_f32 v[62:63], v[62:63], v[174:175]
	v_pk_mul_f32 v[64:65], v[64:65], v[176:177]
	v_pk_mul_f32 v[58:59], v[58:59], v[178:179]
	v_pk_mul_f32 v[60:61], v[60:61], v[180:181]
.Lp2q_ns0:
	v_cvt_pk_bf16_f32 v126, v126, v127
	v_cvt_pk_bf16_f32 v127, v128, v129
	v_cvt_pk_bf16_f32 v128, v122, v123
	v_cvt_pk_bf16_f32 v129, v124, v125
	v_cvt_pk_bf16_f32 v62, v62, v63
	v_cvt_pk_bf16_f32 v63, v64, v65
	v_cvt_pk_bf16_f32 v64, v58, v59
	v_cvt_pk_bf16_f32 v65, v60, v61
	global_store_dwordx4 v[160:161], v[126:129], off sc1
	global_store_dwordx4 v[160:161], v[62:65], off offset:256 sc1
	s_mov_b32 s0, 0x16800
	v_lshl_add_u64 v[160:161], v[160:161], 0, s[0:1]
	s_and_b64 vcc, exec, s[88:89]
	s_cbranch_vccz .Lp2q_nsc1
	v_pk_mul_f32 v[118:119], v[158:159], v[118:119]
	v_pk_mul_f32 v[120:121], v[158:159], v[120:121]
	v_pk_mul_f32 v[114:115], v[158:159], v[114:115]
	v_pk_mul_f32 v[116:117], v[158:159], v[116:117]
	v_pk_mul_f32 v[54:55], v[158:159], v[54:55]
	v_pk_mul_f32 v[56:57], v[158:159], v[56:57]
	v_pk_mul_f32 v[50:51], v[158:159], v[50:51]
	v_pk_mul_f32 v[52:53], v[158:159], v[52:53]
.Lp2q_nsc1:
	s_and_b64 vcc, exec, s[90:91]
	s_cbranch_vccz .Lp2q_ns1
	v_pk_mul_f32 v[166:167], v[118:119], v[164:165]
	v_pk_mul_f32 v[168:169], v[120:121], v[164:165]
	v_pk_mul_f32 v[170:171], v[114:115], v[164:165]
	v_pk_mul_f32 v[172:173], v[116:117], v[164:165]
	v_pk_mul_f32 v[174:175], v[54:55], v[164:165]
	v_pk_mul_f32 v[176:177], v[56:57], v[164:165]
	v_pk_mul_f32 v[178:179], v[50:51], v[164:165]
	v_pk_mul_f32 v[180:181], v[52:53], v[164:165]
	v_exp_f32_e32 v166, v166
	v_exp_f32_e32 v167, v167
	v_exp_f32_e32 v168, v168
	v_exp_f32_e32 v169, v169
	v_exp_f32_e32 v170, v170
	v_exp_f32_e32 v171, v171
	v_exp_f32_e32 v172, v172
	v_exp_f32_e32 v173, v173
	v_exp_f32_e32 v174, v174
	v_exp_f32_e32 v175, v175
	v_exp_f32_e32 v176, v176
	v_exp_f32_e32 v177, v177
	v_exp_f32_e32 v178, v178
	v_exp_f32_e32 v179, v179
	v_exp_f32_e32 v180, v180
	v_exp_f32_e32 v181, v181
	v_pk_add_f32 v[166:167], v[166:167], 1.0 op_sel_hi:[1,0]
	v_pk_add_f32 v[168:169], v[168:169], 1.0 op_sel_hi:[1,0]
	v_pk_add_f32 v[170:171], v[170:171], 1.0 op_sel_hi:[1,0]
	v_pk_add_f32 v[172:173], v[172:173], 1.0 op_sel_hi:[1,0]
	v_pk_add_f32 v[174:175], v[174:175], 1.0 op_sel_hi:[1,0]
	v_pk_add_f32 v[176:177], v[176:177], 1.0 op_sel_hi:[1,0]
	v_pk_add_f32 v[178:179], v[178:179], 1.0 op_sel_hi:[1,0]
	v_pk_add_f32 v[180:181], v[180:181], 1.0 op_sel_hi:[1,0]
	v_rcp_f32_e32 v166, v166
	v_rcp_f32_e32 v167, v167
	v_rcp_f32_e32 v168, v168
	v_rcp_f32_e32 v169, v169
	v_rcp_f32_e32 v170, v170
	v_rcp_f32_e32 v171, v171
	v_rcp_f32_e32 v172, v172
	v_rcp_f32_e32 v173, v173
	v_rcp_f32_e32 v174, v174
	v_rcp_f32_e32 v175, v175
	v_rcp_f32_e32 v176, v176
	v_rcp_f32_e32 v177, v177
	v_rcp_f32_e32 v178, v178
	v_rcp_f32_e32 v179, v179
	v_rcp_f32_e32 v180, v180
	v_rcp_f32_e32 v181, v181
	v_pk_mul_f32 v[118:119], v[118:119], v[166:167]
	v_pk_mul_f32 v[120:121], v[120:121], v[168:169]
	v_pk_mul_f32 v[114:115], v[114:115], v[170:171]
	v_pk_mul_f32 v[116:117], v[116:117], v[172:173]
	v_pk_mul_f32 v[54:55], v[54:55], v[174:175]
	v_pk_mul_f32 v[56:57], v[56:57], v[176:177]
	v_pk_mul_f32 v[50:51], v[50:51], v[178:179]
	v_pk_mul_f32 v[52:53], v[52:53], v[180:181]
; __device__ __forceinline__ unsigned cvt_pk_bf16(float lo, float hi) { unsigned r; asm volatile("v_cvt_pk_bf16_f32 %0, %1, %2" : "=v"(r) : "v"(lo), "v"(hi)); return r; }
; __device__ __forceinline__ float silu_f(float x) { return x * __builtin_amdgcn_rcpf(1.0f + __expf(-x)); }
;     __device__ __forceinline__ void operator()(const f32x4 (&acc)[2][2][4][2], const Unit& u, int wr, int wc, int fr, int fq) const {
;     ...
;             const int col0 = u.pn * BM + bj * HALF + wc * 32 + 8 * fq;
;             if (col0 >= 2880) continue;
;             const float sc = (col0 < 256) ? 0.125f : 1.0f;
; #pragma unroll
;             for (int ai = 0; ai < 2; ++ai)
; #pragma unroll
;                 for (int m = 0; m < 4; ++m) {
;                     f32x4 v0 = acc[ai][bj][m][0] * sc, v1 = acc[ai][bj][m][1] * sc;
;                     if (col0 >= 1024 && col0 < 2048) {
; #pragma unroll
;                         for (int e = 0; e < 4; ++e) { v0[e] = silu_f(v0[e]); v1[e] = silu_f(v1[e]); } }
;                     u32x4 w; w.x = cvt_pk_bf16(v0[0], v0[1]); w.y = cvt_pk_bf16(v0[2], v0[3]); w.z = cvt_pk_bf16(v1[0], v1[1]); w.w = cvt_pk_bf16(v1[2], v1[3]);
;                     *(u32x4*)(O + (size_t)(row0 + ai * HALF + m * 16) * 2880 + col0) = w;
.Lp2q_ns1:
	v_cvt_pk_bf16_f32 v118, v118, v119
	v_cvt_pk_bf16_f32 v119, v120, v121
	v_cvt_pk_bf16_f32 v120, v114, v115
	v_cvt_pk_bf16_f32 v121, v116, v117
	v_cvt_pk_bf16_f32 v54, v54, v55
	v_cvt_pk_bf16_f32 v55, v56, v57
	v_cvt_pk_bf16_f32 v56, v50, v51
	v_cvt_pk_bf16_f32 v57, v52, v53
	global_store_dwordx4 v[160:161], v[118:121], off sc1
	global_store_dwordx4 v[160:161], v[54:57], off offset:256 sc1
	s_mov_b32 s0, 0x16800
	v_lshl_add_u64 v[160:161], v[160:161], 0, s[0:1]
	s_and_b64 vcc, exec, s[88:89]
	s_cbranch_vccz .Lp2q_nsc2
	v_pk_mul_f32 v[110:111], v[158:159], v[110:111]
	v_pk_mul_f32 v[112:113], v[158:159], v[112:113]
	v_pk_mul_f32 v[106:107], v[158:159], v[106:107]
	v_pk_mul_f32 v[108:109], v[158:159], v[108:109]
	v_pk_mul_f32 v[46:47], v[158:159], v[46:47]
	v_pk_mul_f32 v[48:49], v[158:159], v[48:49]
	v_pk_mul_f32 v[42:43], v[158:159], v[42:43]
	v_pk_mul_f32 v[44:45], v[158:159], v[44:45]
.Lp2q_nsc2:
	s_and_b64 vcc, exec, s[90:91]
	s_cbranch_vccz .Lp2q_ns2
	v_pk_mul_f32 v[166:167], v[110:111], v[164:165]
	v_pk_mul_f32 v[168:169], v[112:113], v[164:165]
	v_pk_mul_f32 v[170:171], v[106:107], v[164:165]
	v_pk_mul_f32 v[172:173], v[108:109], v[164:165]
	v_pk_mul_f32 v[174:175], v[46:47], v[164:165]
	v_pk_mul_f32 v[176:177], v[48:49], v[164:165]
	v_pk_mul_f32 v[178:179], v[42:43], v[164:165]
	v_pk_mul_f32 v[180:181], v[44:45], v[164:165]
	v_exp_f32_e32 v166, v166
	v_exp_f32_e32 v167, v167
	v_exp_f32_e32 v168, v168
	v_exp_f32_e32 v169, v169
	v_exp_f32_e32 v170, v170
	v_exp_f32_e32 v171, v171
	v_exp_f32_e32 v172, v172
	v_exp_f32_e32 v173, v173
	v_exp_f32_e32 v174, v174
	v_exp_f32_e32 v175, v175
	v_exp_f32_e32 v176, v176
	v_exp_f32_e32 v177, v177
	v_exp_f32_e32 v178, v178
	v_exp_f32_e32 v179, v179
	v_exp_f32_e32 v180, v180
	v_exp_f32_e32 v181, v181
	v_pk_add_f32 v[166:167], v[166:167], 1.0 op_sel_hi:[1,0]
	v_pk_add_f32 v[168:169], v[168:169], 1.0 op_sel_hi:[1,0]
	v_pk_add_f32 v[170:171], v[170:171], 1.0 op_sel_hi:[1,0]
	v_pk_add_f32 v[172:173], v[172:173], 1.0 op_sel_hi:[1,0]
	v_pk_add_f32 v[174:175], v[174:175], 1.0 op_sel_hi:[1,0]
	v_pk_add_f32 v[176:177], v[176:177], 1.0 op_sel_hi:[1,0]
	v_pk_add_f32 v[178:179], v[178:179], 1.0 op_sel_hi:[1,0]
	v_pk_add_f32 v[180:181], v[180:181], 1.0 op_sel_hi:[1,0]
	v_rcp_f32_e32 v166, v166
	v_rcp_f32_e32 v167, v167
	v_rcp_f32_e32 v168, v168
	v_rcp_f32_e32 v169, v169
	v_rcp_f32_e32 v170, v170
	v_rcp_f32_e32 v171, v171
	v_rcp_f32_e32 v172, v172
	v_rcp_f32_e32 v173, v173
	v_rcp_f32_e32 v174, v174
	v_rcp_f32_e32 v175, v175
	v_rcp_f32_e32 v176, v176
	v_rcp_f32_e32 v177, v177
	v_rcp_f32_e32 v178, v178
	v_rcp_f32_e32 v179, v179
	v_rcp_f32_e32 v180, v180
	v_rcp_f32_e32 v181, v181
	v_pk_mul_f32 v[110:111], v[110:111], v[166:167]
	v_pk_mul_f32 v[112:113], v[112:113], v[168:169]
	v_pk_mul_f32 v[106:107], v[106:107], v[170:171]
	v_pk_mul_f32 v[108:109], v[108:109], v[172:173]
	v_pk_mul_f32 v[46:47], v[46:47], v[174:175]
	v_pk_mul_f32 v[48:49], v[48:49], v[176:177]
	v_pk_mul_f32 v[42:43], v[42:43], v[178:179]
	v_pk_mul_f32 v[44:45], v[44:45], v[180:181]
.Lp2q_ns2:
	v_cvt_pk_bf16_f32 v110, v110, v111
	v_cvt_pk_bf16_f32 v111, v112, v113
	v_cvt_pk_bf16_f32 v112, v106, v107
	v_cvt_pk_bf16_f32 v113, v108, v109
	v_cvt_pk_bf16_f32 v46, v46, v47
	v_cvt_pk_bf16_f32 v47, v48, v49
	v_cvt_pk_bf16_f32 v48, v42, v43
	v_cvt_pk_bf16_f32 v49, v44, v45
	global_store_dwordx4 v[160:161], v[110:113], off sc1
	global_store_dwordx4 v[160:161], v[46:49], off offset:256 sc1
	s_mov_b32 s0, 0x16800
	v_lshl_add_u64 v[160:161], v[160:161], 0, s[0:1]
	s_and_b64 vcc, exec, s[88:89]
	s_cbranch_vccz .Lp2q_nsc3
	v_pk_mul_f32 v[102:103], v[158:159], v[102:103]
	v_pk_mul_f32 v[104:105], v[158:159], v[104:105]
	v_pk_mul_f32 v[98:99], v[158:159], v[98:99]
	v_pk_mul_f32 v[100:101], v[158:159], v[100:101]
	v_pk_mul_f32 v[38:39], v[158:159], v[38:39]
	v_pk_mul_f32 v[40:41], v[158:159], v[40:41]
	v_pk_mul_f32 v[34:35], v[158:159], v[34:35]
	v_pk_mul_f32 v[36:37], v[158:159], v[36:37]
.Lp2q_nsc3:
	s_and_b64 vcc, exec, s[90:91]
	s_cbranch_vccz .Lp2q_ns3
	v_pk_mul_f32 v[166:167], v[102:103], v[164:165]
	v_pk_mul_f32 v[168:169], v[104:105], v[164:165]
	v_pk_mul_f32 v[170:171], v[98:99], v[164:165]
	v_pk_mul_f32 v[172:173], v[100:101], v[164:165]
	v_pk_mul_f32 v[174:175], v[38:39], v[164:165]
	v_pk_mul_f32 v[176:177], v[40:41], v[164:165]
	v_pk_mul_f32 v[178:179], v[34:35], v[164:165]
	v_pk_mul_f32 v[180:181], v[36:37], v[164:165]
	v_exp_f32_e32 v166, v166
	v_exp_f32_e32 v167, v167
	v_exp_f32_e32 v168, v168
	v_exp_f32_e32 v169, v169
	v_exp_f32_e32 v170, v170
	v_exp_f32_e32 v171, v171
	v_exp_f32_e32 v172, v172
	v_exp_f32_e32 v173, v173
	v_exp_f32_e32 v174, v174
	v_exp_f32_e32 v175, v175
	v_exp_f32_e32 v176, v176
	v_exp_f32_e32 v177, v177
	v_exp_f32_e32 v178, v178
	v_exp_f32_e32 v179, v179
	v_exp_f32_e32 v180, v180
	v_exp_f32_e32 v181, v181
	v_pk_add_f32 v[166:167], v[166:167], 1.0 op_sel_hi:[1,0]
	v_pk_add_f32 v[168:169], v[168:169], 1.0 op_sel_hi:[1,0]
	v_pk_add_f32 v[170:171], v[170:171], 1.0 op_sel_hi:[1,0]
	v_pk_add_f32 v[172:173], v[172:173], 1.0 op_sel_hi:[1,0]
	v_pk_add_f32 v[174:175], v[174:175], 1.0 op_sel_hi:[1,0]
	v_pk_add_f32 v[176:177], v[176:177], 1.0 op_sel_hi:[1,0]
	v_pk_add_f32 v[178:179], v[178:179], 1.0 op_sel_hi:[1,0]
	v_pk_add_f32 v[180:181], v[180:181], 1.0 op_sel_hi:[1,0]
	v_rcp_f32_e32 v166, v166
	v_rcp_f32_e32 v167, v167
	v_rcp_f32_e32 v168, v168
	v_rcp_f32_e32 v169, v169
	v_rcp_f32_e32 v170, v170
	v_rcp_f32_e32 v171, v171
	v_rcp_f32_e32 v172, v172
	v_rcp_f32_e32 v173, v173
	v_rcp_f32_e32 v174, v174
	v_rcp_f32_e32 v175, v175
	v_rcp_f32_e32 v176, v176
	v_rcp_f32_e32 v177, v177
	v_rcp_f32_e32 v178, v178
	v_rcp_f32_e32 v179, v179
	v_rcp_f32_e32 v180, v180
	v_rcp_f32_e32 v181, v181
	v_pk_mul_f32 v[102:103], v[102:103], v[166:167]
	v_pk_mul_f32 v[104:105], v[104:105], v[168:169]
	v_pk_mul_f32 v[98:99], v[98:99], v[170:171]
	v_pk_mul_f32 v[100:101], v[100:101], v[172:173]
	v_pk_mul_f32 v[38:39], v[38:39], v[174:175]
	v_pk_mul_f32 v[40:41], v[40:41], v[176:177]
	v_pk_mul_f32 v[34:35], v[34:35], v[178:179]
	v_pk_mul_f32 v[36:37], v[36:37], v[180:181]
; __device__ __forceinline__ unsigned cvt_pk_bf16(float lo, float hi) { unsigned r; asm volatile("v_cvt_pk_bf16_f32 %0, %1, %2" : "=v"(r) : "v"(lo), "v"(hi)); return r; }
; __device__ __forceinline__ float silu_f(float x) { return x * __builtin_amdgcn_rcpf(1.0f + __expf(-x)); }
;     __device__ __forceinline__ void operator()(const f32x4 (&acc)[2][2][4][2], const Unit& u, int wr, int wc, int fr, int fq) const {
;     ...
;             const int col0 = u.pn * BM + bj * HALF + wc * 32 + 8 * fq;
;             if (col0 >= 2880) continue;
;             const float sc = (col0 < 256) ? 0.125f : 1.0f;
; #pragma unroll
;             for (int ai = 0; ai < 2; ++ai)
; #pragma unroll
;                 for (int m = 0; m < 4; ++m) {
;                     f32x4 v0 = acc[ai][bj][m][0] * sc, v1 = acc[ai][bj][m][1] * sc;
;                     if (col0 >= 1024 && col0 < 2048) {
; #pragma unroll
;                         for (int e = 0; e < 4; ++e) { v0[e] = silu_f(v0[e]); v1[e] = silu_f(v1[e]); } }
;                     u32x4 w; w.x = cvt_pk_bf16(v0[0], v0[1]); w.y = cvt_pk_bf16(v0[2], v0[3]); w.z = cvt_pk_bf16(v1[0], v1[1]); w.w = cvt_pk_bf16(v1[2], v1[3]);
;                     *(u32x4*)(O + (size_t)(row0 + ai * HALF + m * 16) * 2880 + col0) = w;
.Lp2q_ns3:
	v_cvt_pk_bf16_f32 v102, v102, v103
	v_cvt_pk_bf16_f32 v103, v104, v105
	v_cvt_pk_bf16_f32 v104, v98, v99
	v_cvt_pk_bf16_f32 v105, v100, v101
	v_cvt_pk_bf16_f32 v38, v38, v39
	v_cvt_pk_bf16_f32 v39, v40, v41
	v_cvt_pk_bf16_f32 v40, v34, v35
	v_cvt_pk_bf16_f32 v41, v36, v37
	global_store_dwordx4 v[160:161], v[102:105], off sc1
	global_store_dwordx4 v[160:161], v[38:41], off offset:256 sc1
	s_mov_b32 s0, 0x70800
	v_lshl_add_u64 v[160:161], v[160:161], 0, s[0:1]
	s_and_b64 vcc, exec, s[88:89]
	s_cbranch_vccz .Lp2q_nsc4
	v_pk_mul_f32 v[94:95], v[158:159], v[94:95]
	v_pk_mul_f32 v[96:97], v[158:159], v[96:97]
	v_pk_mul_f32 v[90:91], v[158:159], v[90:91]
	v_pk_mul_f32 v[92:93], v[158:159], v[92:93]
	v_pk_mul_f32 v[30:31], v[158:159], v[30:31]
	v_pk_mul_f32 v[32:33], v[158:159], v[32:33]
	v_pk_mul_f32 v[26:27], v[158:159], v[26:27]
	v_pk_mul_f32 v[28:29], v[158:159], v[28:29]
.Lp2q_nsc4:
	s_and_b64 vcc, exec, s[90:91]
	s_cbranch_vccz .Lp2q_ns4
	v_pk_mul_f32 v[166:167], v[94:95], v[164:165]
	v_pk_mul_f32 v[168:169], v[96:97], v[164:165]
	v_pk_mul_f32 v[170:171], v[90:91], v[164:165]
	v_pk_mul_f32 v[172:173], v[92:93], v[164:165]
	v_pk_mul_f32 v[174:175], v[30:31], v[164:165]
	v_pk_mul_f32 v[176:177], v[32:33], v[164:165]
	v_pk_mul_f32 v[178:179], v[26:27], v[164:165]
	v_pk_mul_f32 v[180:181], v[28:29], v[164:165]
	v_exp_f32_e32 v166, v166
	v_exp_f32_e32 v167, v167
	v_exp_f32_e32 v168, v168
	v_exp_f32_e32 v169, v169
	v_exp_f32_e32 v170, v170
	v_exp_f32_e32 v171, v171
	v_exp_f32_e32 v172, v172
	v_exp_f32_e32 v173, v173
	v_exp_f32_e32 v174, v174
	v_exp_f32_e32 v175, v175
	v_exp_f32_e32 v176, v176
	v_exp_f32_e32 v177, v177
	v_exp_f32_e32 v178, v178
	v_exp_f32_e32 v179, v179
	v_exp_f32_e32 v180, v180
	v_exp_f32_e32 v181, v181
	v_pk_add_f32 v[166:167], v[166:167], 1.0 op_sel_hi:[1,0]
	v_pk_add_f32 v[168:169], v[168:169], 1.0 op_sel_hi:[1,0]
	v_pk_add_f32 v[170:171], v[170:171], 1.0 op_sel_hi:[1,0]
	v_pk_add_f32 v[172:173], v[172:173], 1.0 op_sel_hi:[1,0]
	v_pk_add_f32 v[174:175], v[174:175], 1.0 op_sel_hi:[1,0]
	v_pk_add_f32 v[176:177], v[176:177], 1.0 op_sel_hi:[1,0]
	v_pk_add_f32 v[178:179], v[178:179], 1.0 op_sel_hi:[1,0]
	v_pk_add_f32 v[180:181], v[180:181], 1.0 op_sel_hi:[1,0]
	v_rcp_f32_e32 v166, v166
	v_rcp_f32_e32 v167, v167
	v_rcp_f32_e32 v168, v168
	v_rcp_f32_e32 v169, v169
	v_rcp_f32_e32 v170, v170
	v_rcp_f32_e32 v171, v171
	v_rcp_f32_e32 v172, v172
	v_rcp_f32_e32 v173, v173
	v_rcp_f32_e32 v174, v174
	v_rcp_f32_e32 v175, v175
	v_rcp_f32_e32 v176, v176
	v_rcp_f32_e32 v177, v177
	v_rcp_f32_e32 v178, v178
	v_rcp_f32_e32 v179, v179
	v_rcp_f32_e32 v180, v180
	v_rcp_f32_e32 v181, v181
	v_pk_mul_f32 v[94:95], v[94:95], v[166:167]
	v_pk_mul_f32 v[96:97], v[96:97], v[168:169]
	v_pk_mul_f32 v[90:91], v[90:91], v[170:171]
	v_pk_mul_f32 v[92:93], v[92:93], v[172:173]
	v_pk_mul_f32 v[30:31], v[30:31], v[174:175]
	v_pk_mul_f32 v[32:33], v[32:33], v[176:177]
	v_pk_mul_f32 v[26:27], v[26:27], v[178:179]
	v_pk_mul_f32 v[28:29], v[28:29], v[180:181]
.Lp2q_ns4:
	v_cvt_pk_bf16_f32 v94, v94, v95
	v_cvt_pk_bf16_f32 v95, v96, v97
	v_cvt_pk_bf16_f32 v96, v90, v91
	v_cvt_pk_bf16_f32 v97, v92, v93
	v_cvt_pk_bf16_f32 v30, v30, v31
	v_cvt_pk_bf16_f32 v31, v32, v33
	v_cvt_pk_bf16_f32 v32, v26, v27
	v_cvt_pk_bf16_f32 v33, v28, v29
	global_store_dwordx4 v[160:161], v[94:97], off sc1
	global_store_dwordx4 v[160:161], v[30:33], off offset:256 sc1
	s_mov_b32 s0, 0x16800
	v_lshl_add_u64 v[160:161], v[160:161], 0, s[0:1]
	s_and_b64 vcc, exec, s[88:89]
	s_cbranch_vccz .Lp2q_nsc5
	v_pk_mul_f32 v[86:87], v[158:159], v[86:87]
	v_pk_mul_f32 v[88:89], v[158:159], v[88:89]
	v_pk_mul_f32 v[82:83], v[158:159], v[82:83]
	v_pk_mul_f32 v[84:85], v[158:159], v[84:85]
	v_pk_mul_f32 v[22:23], v[158:159], v[22:23]
	v_pk_mul_f32 v[24:25], v[158:159], v[24:25]
	v_pk_mul_f32 v[18:19], v[158:159], v[18:19]
	v_pk_mul_f32 v[20:21], v[158:159], v[20:21]
.Lp2q_nsc5:
	s_and_b64 vcc, exec, s[90:91]
	s_cbranch_vccz .Lp2q_ns5
	v_pk_mul_f32 v[166:167], v[86:87], v[164:165]
	v_pk_mul_f32 v[168:169], v[88:89], v[164:165]
	v_pk_mul_f32 v[170:171], v[82:83], v[164:165]
	v_pk_mul_f32 v[172:173], v[84:85], v[164:165]
	v_pk_mul_f32 v[174:175], v[22:23], v[164:165]
	v_pk_mul_f32 v[176:177], v[24:25], v[164:165]
	v_pk_mul_f32 v[178:179], v[18:19], v[164:165]
	v_pk_mul_f32 v[180:181], v[20:21], v[164:165]
	v_exp_f32_e32 v166, v166
	v_exp_f32_e32 v167, v167
	v_exp_f32_e32 v168, v168
	v_exp_f32_e32 v169, v169
	v_exp_f32_e32 v170, v170
	v_exp_f32_e32 v171, v171
	v_exp_f32_e32 v172, v172
	v_exp_f32_e32 v173, v173
	v_exp_f32_e32 v174, v174
	v_exp_f32_e32 v175, v175
	v_exp_f32_e32 v176, v176
	v_exp_f32_e32 v177, v177
	v_exp_f32_e32 v178, v178
	v_exp_f32_e32 v179, v179
	v_exp_f32_e32 v180, v180
	v_exp_f32_e32 v181, v181
	v_pk_add_f32 v[166:167], v[166:167], 1.0 op_sel_hi:[1,0]
	v_pk_add_f32 v[168:169], v[168:169], 1.0 op_sel_hi:[1,0]
	v_pk_add_f32 v[170:171], v[170:171], 1.0 op_sel_hi:[1,0]
	v_pk_add_f32 v[172:173], v[172:173], 1.0 op_sel_hi:[1,0]
	v_pk_add_f32 v[174:175], v[174:175], 1.0 op_sel_hi:[1,0]
	v_pk_add_f32 v[176:177], v[176:177], 1.0 op_sel_hi:[1,0]
	v_pk_add_f32 v[178:179], v[178:179], 1.0 op_sel_hi:[1,0]
	v_pk_add_f32 v[180:181], v[180:181], 1.0 op_sel_hi:[1,0]
	v_rcp_f32_e32 v166, v166
	v_rcp_f32_e32 v167, v167
	v_rcp_f32_e32 v168, v168
	v_rcp_f32_e32 v169, v169
	v_rcp_f32_e32 v170, v170
	v_rcp_f32_e32 v171, v171
	v_rcp_f32_e32 v172, v172
	v_rcp_f32_e32 v173, v173
	v_rcp_f32_e32 v174, v174
	v_rcp_f32_e32 v175, v175
	v_rcp_f32_e32 v176, v176
	v_rcp_f32_e32 v177, v177
	v_rcp_f32_e32 v178, v178
	v_rcp_f32_e32 v179, v179
	v_rcp_f32_e32 v180, v180
	v_rcp_f32_e32 v181, v181
	v_pk_mul_f32 v[86:87], v[86:87], v[166:167]
	v_pk_mul_f32 v[88:89], v[88:89], v[168:169]
	v_pk_mul_f32 v[82:83], v[82:83], v[170:171]
	v_pk_mul_f32 v[84:85], v[84:85], v[172:173]
	v_pk_mul_f32 v[22:23], v[22:23], v[174:175]
	v_pk_mul_f32 v[24:25], v[24:25], v[176:177]
	v_pk_mul_f32 v[18:19], v[18:19], v[178:179]
	v_pk_mul_f32 v[20:21], v[20:21], v[180:181]
; __device__ __forceinline__ unsigned cvt_pk_bf16(float lo, float hi) { unsigned r; asm volatile("v_cvt_pk_bf16_f32 %0, %1, %2" : "=v"(r) : "v"(lo), "v"(hi)); return r; }
; __device__ __forceinline__ float silu_f(float x) { return x * __builtin_amdgcn_rcpf(1.0f + __expf(-x)); }
;     __device__ __forceinline__ void operator()(const f32x4 (&acc)[2][2][4][2], const Unit& u, int wr, int wc, int fr, int fq) const {
;     ...
;             const int col0 = u.pn * BM + bj * HALF + wc * 32 + 8 * fq;
;             if (col0 >= 2880) continue;
;             const float sc = (col0 < 256) ? 0.125f : 1.0f;
; #pragma unroll
;             for (int ai = 0; ai < 2; ++ai)
; #pragma unroll
;                 for (int m = 0; m < 4; ++m) {
;                     f32x4 v0 = acc[ai][bj][m][0] * sc, v1 = acc[ai][bj][m][1] * sc;
;                     if (col0 >= 1024 && col0 < 2048) {
; #pragma unroll
;                         for (int e = 0; e < 4; ++e) { v0[e] = silu_f(v0[e]); v1[e] = silu_f(v1[e]); } }
;                     u32x4 w; w.x = cvt_pk_bf16(v0[0], v0[1]); w.y = cvt_pk_bf16(v0[2], v0[3]); w.z = cvt_pk_bf16(v1[0], v1[1]); w.w = cvt_pk_bf16(v1[2], v1[3]);
;                     *(u32x4*)(O + (size_t)(row0 + ai * HALF + m * 16) * 2880 + col0) = w;
.Lp2q_ns5:
	v_cvt_pk_bf16_f32 v86, v86, v87
	v_cvt_pk_bf16_f32 v87, v88, v89
	v_cvt_pk_bf16_f32 v88, v82, v83
	v_cvt_pk_bf16_f32 v89, v84, v85
	v_cvt_pk_bf16_f32 v22, v22, v23
	v_cvt_pk_bf16_f32 v23, v24, v25
	v_cvt_pk_bf16_f32 v24, v18, v19
	v_cvt_pk_bf16_f32 v25, v20, v21
	global_store_dwordx4 v[160:161], v[86:89], off sc1
	global_store_dwordx4 v[160:161], v[22:25], off offset:256 sc1
	s_mov_b32 s0, 0x16800
	v_lshl_add_u64 v[160:161], v[160:161], 0, s[0:1]
	s_and_b64 vcc, exec, s[88:89]
	s_cbranch_vccz .Lp2q_nsc6
	v_pk_mul_f32 v[78:79], v[158:159], v[78:79]
	v_pk_mul_f32 v[80:81], v[158:159], v[80:81]
	v_pk_mul_f32 v[74:75], v[158:159], v[74:75]
	v_pk_mul_f32 v[76:77], v[158:159], v[76:77]
	v_pk_mul_f32 v[14:15], v[158:159], v[14:15]
	v_pk_mul_f32 v[16:17], v[158:159], v[16:17]
	v_pk_mul_f32 v[10:11], v[158:159], v[10:11]
	v_pk_mul_f32 v[12:13], v[158:159], v[12:13]
.Lp2q_nsc6:
	s_and_b64 vcc, exec, s[90:91]
	s_cbranch_vccz .Lp2q_ns6
	v_pk_mul_f32 v[166:167], v[78:79], v[164:165]
	v_pk_mul_f32 v[168:169], v[80:81], v[164:165]
	v_pk_mul_f32 v[170:171], v[74:75], v[164:165]
	v_pk_mul_f32 v[172:173], v[76:77], v[164:165]
	v_pk_mul_f32 v[174:175], v[14:15], v[164:165]
	v_pk_mul_f32 v[176:177], v[16:17], v[164:165]
	v_pk_mul_f32 v[178:179], v[10:11], v[164:165]
	v_pk_mul_f32 v[180:181], v[12:13], v[164:165]
	v_exp_f32_e32 v166, v166
	v_exp_f32_e32 v167, v167
	v_exp_f32_e32 v168, v168
	v_exp_f32_e32 v169, v169
	v_exp_f32_e32 v170, v170
	v_exp_f32_e32 v171, v171
	v_exp_f32_e32 v172, v172
	v_exp_f32_e32 v173, v173
	v_exp_f32_e32 v174, v174
	v_exp_f32_e32 v175, v175
	v_exp_f32_e32 v176, v176
	v_exp_f32_e32 v177, v177
	v_exp_f32_e32 v178, v178
	v_exp_f32_e32 v179, v179
	v_exp_f32_e32 v180, v180
	v_exp_f32_e32 v181, v181
	v_pk_add_f32 v[166:167], v[166:167], 1.0 op_sel_hi:[1,0]
	v_pk_add_f32 v[168:169], v[168:169], 1.0 op_sel_hi:[1,0]
	v_pk_add_f32 v[170:171], v[170:171], 1.0 op_sel_hi:[1,0]
	v_pk_add_f32 v[172:173], v[172:173], 1.0 op_sel_hi:[1,0]
	v_pk_add_f32 v[174:175], v[174:175], 1.0 op_sel_hi:[1,0]
	v_pk_add_f32 v[176:177], v[176:177], 1.0 op_sel_hi:[1,0]
	v_pk_add_f32 v[178:179], v[178:179], 1.0 op_sel_hi:[1,0]
	v_pk_add_f32 v[180:181], v[180:181], 1.0 op_sel_hi:[1,0]
	v_rcp_f32_e32 v166, v166
	v_rcp_f32_e32 v167, v167
	v_rcp_f32_e32 v168, v168
	v_rcp_f32_e32 v169, v169
	v_rcp_f32_e32 v170, v170
	v_rcp_f32_e32 v171, v171
	v_rcp_f32_e32 v172, v172
	v_rcp_f32_e32 v173, v173
	v_rcp_f32_e32 v174, v174
	v_rcp_f32_e32 v175, v175
	v_rcp_f32_e32 v176, v176
	v_rcp_f32_e32 v177, v177
	v_rcp_f32_e32 v178, v178
	v_rcp_f32_e32 v179, v179
	v_rcp_f32_e32 v180, v180
	v_rcp_f32_e32 v181, v181
	v_pk_mul_f32 v[78:79], v[78:79], v[166:167]
	v_pk_mul_f32 v[80:81], v[80:81], v[168:169]
	v_pk_mul_f32 v[74:75], v[74:75], v[170:171]
	v_pk_mul_f32 v[76:77], v[76:77], v[172:173]
	v_pk_mul_f32 v[14:15], v[14:15], v[174:175]
	v_pk_mul_f32 v[16:17], v[16:17], v[176:177]
	v_pk_mul_f32 v[10:11], v[10:11], v[178:179]
	v_pk_mul_f32 v[12:13], v[12:13], v[180:181]
.Lp2q_ns6:
	v_cvt_pk_bf16_f32 v78, v78, v79
	v_cvt_pk_bf16_f32 v79, v80, v81
	v_cvt_pk_bf16_f32 v80, v74, v75
	v_cvt_pk_bf16_f32 v81, v76, v77
	v_cvt_pk_bf16_f32 v14, v14, v15
	v_cvt_pk_bf16_f32 v15, v16, v17
	v_cvt_pk_bf16_f32 v16, v10, v11
	v_cvt_pk_bf16_f32 v17, v12, v13
	global_store_dwordx4 v[160:161], v[78:81], off sc1
	global_store_dwordx4 v[160:161], v[14:17], off offset:256 sc1
	s_mov_b32 s0, 0x16800
	v_lshl_add_u64 v[160:161], v[160:161], 0, s[0:1]
	s_and_b64 vcc, exec, s[88:89]
	s_cbranch_vccz .Lp2q_nsc7
	v_pk_mul_f32 v[70:71], v[158:159], v[70:71]
	v_pk_mul_f32 v[72:73], v[158:159], v[72:73]
	v_pk_mul_f32 v[66:67], v[158:159], v[66:67]
	v_pk_mul_f32 v[68:69], v[158:159], v[68:69]
	v_pk_mul_f32 v[6:7], v[158:159], v[6:7]
	v_pk_mul_f32 v[8:9], v[158:159], v[8:9]
	v_pk_mul_f32 v[2:3], v[158:159], v[2:3]
	v_pk_mul_f32 v[4:5], v[158:159], v[4:5]
.Lp2q_nsc7:
	s_and_b64 vcc, exec, s[90:91]
	s_cbranch_vccz .Lp2q_ns7
	v_pk_mul_f32 v[166:167], v[70:71], v[164:165]
	v_pk_mul_f32 v[168:169], v[72:73], v[164:165]
	v_pk_mul_f32 v[170:171], v[66:67], v[164:165]
	v_pk_mul_f32 v[172:173], v[68:69], v[164:165]
	v_pk_mul_f32 v[174:175], v[6:7], v[164:165]
	v_pk_mul_f32 v[176:177], v[8:9], v[164:165]
	v_pk_mul_f32 v[178:179], v[2:3], v[164:165]
	v_pk_mul_f32 v[180:181], v[4:5], v[164:165]
	v_exp_f32_e32 v166, v166
	v_exp_f32_e32 v167, v167
	v_exp_f32_e32 v168, v168
	v_exp_f32_e32 v169, v169
	v_exp_f32_e32 v170, v170
	v_exp_f32_e32 v171, v171
	v_exp_f32_e32 v172, v172
	v_exp_f32_e32 v173, v173
	v_exp_f32_e32 v174, v174
	v_exp_f32_e32 v175, v175
	v_exp_f32_e32 v176, v176
	v_exp_f32_e32 v177, v177
	v_exp_f32_e32 v178, v178
	v_exp_f32_e32 v179, v179
	v_exp_f32_e32 v180, v180
	v_exp_f32_e32 v181, v181
	v_pk_add_f32 v[166:167], v[166:167], 1.0 op_sel_hi:[1,0]
	v_pk_add_f32 v[168:169], v[168:169], 1.0 op_sel_hi:[1,0]
	v_pk_add_f32 v[170:171], v[170:171], 1.0 op_sel_hi:[1,0]
	v_pk_add_f32 v[172:173], v[172:173], 1.0 op_sel_hi:[1,0]
	v_pk_add_f32 v[174:175], v[174:175], 1.0 op_sel_hi:[1,0]
	v_pk_add_f32 v[176:177], v[176:177], 1.0 op_sel_hi:[1,0]
	v_pk_add_f32 v[178:179], v[178:179], 1.0 op_sel_hi:[1,0]
	v_pk_add_f32 v[180:181], v[180:181], 1.0 op_sel_hi:[1,0]
	v_rcp_f32_e32 v166, v166
	v_rcp_f32_e32 v167, v167
	v_rcp_f32_e32 v168, v168
	v_rcp_f32_e32 v169, v169
	v_rcp_f32_e32 v170, v170
	v_rcp_f32_e32 v171, v171
	v_rcp_f32_e32 v172, v172
	v_rcp_f32_e32 v173, v173
	v_rcp_f32_e32 v174, v174
	v_rcp_f32_e32 v175, v175
	v_rcp_f32_e32 v176, v176
	v_rcp_f32_e32 v177, v177
	v_rcp_f32_e32 v178, v178
	v_rcp_f32_e32 v179, v179
	v_rcp_f32_e32 v180, v180
	v_rcp_f32_e32 v181, v181
	v_pk_mul_f32 v[70:71], v[70:71], v[166:167]
	v_pk_mul_f32 v[72:73], v[72:73], v[168:169]
	v_pk_mul_f32 v[66:67], v[66:67], v[170:171]
	v_pk_mul_f32 v[68:69], v[68:69], v[172:173]
	v_pk_mul_f32 v[6:7], v[6:7], v[174:175]
	v_pk_mul_f32 v[8:9], v[8:9], v[176:177]
	v_pk_mul_f32 v[2:3], v[2:3], v[178:179]
	v_pk_mul_f32 v[4:5], v[4:5], v[180:181]
